# attention key-norm reductions: shfl_xor 1/2/4 through ds_bpermute round trips replaced by DPP moves
# speedup vs baseline: 1.0078x; 1.0036x over previous
.LBB0_175:
	s_add_i32 s35, s50, 0xc00
	v_and_b32_e32 v160, 7, v158
	s_mov_b64 s[4:5], -1
	s_cmpk_gt_i32 s35, 0xbff
	v_ashrrev_i32_e32 v159, 3, v158
	v_lshl_add_u32 v152, v160, 4, 0
	v_cmp_eq_u32_e32 vcc, 0, v160
	s_waitcnt vmcnt(4)
	v_lshlrev_b32_e32 v165, 16, v36
	v_and_b32_e32 v185, 0xffff0000, v36
	v_lshlrev_b32_e32 v164, 16, v37
	v_and_b32_e32 v167, 0xffff0000, v37
	v_lshlrev_b32_e32 v162, 16, v38
	v_and_b32_e32 v166, 0xffff0000, v38
	v_lshlrev_b32_e32 v161, 16, v39
	v_and_b32_e32 v163, 0xffff0000, v39
	s_cbranch_scc0 .LBB0_189
	v_mad_u64_u32 v[40:41], s[4:5], v159, s69, v[152:153]
	s_load_dwordx4 s[8:11], s[62:63], 0x58
	s_waitcnt lgkmcnt(0)
	s_barrier
	ds_write_b128 v40, v[36:39]
	v_mul_f32_e32 v40, v185, v185
	v_mul_f32_e32 v41, v167, v167
	v_fmac_f32_e32 v40, v165, v165
	v_fmac_f32_e32 v41, v164, v164
	v_add_f32_e32 v40, v40, v41
	v_mul_f32_e32 v41, v166, v166
	v_fmac_f32_e32 v41, v162, v162
	v_add_f32_e32 v40, v41, v40
	v_mul_f32_e32 v41, v163, v163
	v_fmac_f32_e32 v41, v161, v161
	v_add_f32_e32 v40, v41, v40
	s_nop 1
	v_mov_b32_dpp v41, v40 quad_perm:[1,0,3,2] row_mask:0xf bank_mask:0xf
	s_waitcnt lgkmcnt(0)
	v_add_f32_e32 v40, v40, v41
	s_nop 1
	v_mov_b32_dpp v41, v40 quad_perm:[2,3,0,1] row_mask:0xf bank_mask:0xf
	s_waitcnt lgkmcnt(0)
	v_add_f32_e32 v40, v40, v41
	s_nop 1
	v_mov_b32_dpp v41, v40 row_half_mirror row_mask:0xf bank_mask:0xf
	s_and_saveexec_b64 s[48:49], vcc
	s_cbranch_execz .LBB0_178
	s_waitcnt lgkmcnt(0)
	v_add_f32_e32 v40, v40, v41
	v_fmamk_f32 v40, v40, 0x3c800000, v243
	v_cmp_gt_f32_e64 s[4:5], s88, v40
	v_mul_f32_e32 v41, 0x4b800000, v40
	s_nop 0
	v_cndmask_b32_e64 v40, v40, v41, s[4:5]
	v_rsq_f32_e32 v40, v40
	s_nop 0
	v_mul_f32_e32 v41, 0x45800000, v40
	v_cndmask_b32_e64 v40, v40, v41, s[4:5]
	v_lshl_add_u32 v41, v159, 2, 0
	v_add_u32_e32 v41, 0x11800, v41
	ds_write_b32 v41, v40
.LBB0_178:
	s_or_b64 exec, exec, s[48:49]
	v_and_b32_e32 v43, 0xffff0000, v32
	v_lshlrev_b32_e32 v42, 16, v32
	v_mul_f32_e32 v43, v43, v43
	v_and_b32_e32 v44, 0xffff0000, v33
	v_fmac_f32_e32 v43, v42, v42
	v_lshlrev_b32_e32 v42, 16, v33
	v_mul_f32_e32 v44, v44, v44
	v_fmac_f32_e32 v44, v42, v42
	v_add_f32_e32 v42, v43, v44
	v_and_b32_e32 v44, 0xffff0000, v34
	v_lshlrev_b32_e32 v43, 16, v34
	v_mul_f32_e32 v44, v44, v44
	v_fmac_f32_e32 v44, v43, v43
	v_add_f32_e32 v42, v44, v42
	v_and_b32_e32 v44, 0xffff0000, v35
	v_lshlrev_b32_e32 v43, 16, v35
	v_mul_f32_e32 v44, v44, v44
	v_fmac_f32_e32 v44, v43, v43
	v_add_f32_e32 v42, v44, v42
	s_nop 1
	v_mov_b32_dpp v43, v42 quad_perm:[1,0,3,2] row_mask:0xf bank_mask:0xf
	v_ashrrev_i32_e32 v40, 5, v158
	v_and_b32_e32 v81, 0xff, v158
	v_and_b32_e32 v80, -8, v40
	s_movk_i32 s0, 0x220
	s_waitcnt lgkmcnt(0)
	v_add_f32_e32 v42, v42, v43
	s_nop 1
	v_mov_b32_dpp v43, v42 quad_perm:[2,3,0,1] row_mask:0xf bank_mask:0xf
	v_mul_lo_u32 v41, v80, s0
	v_lshlrev_b32_e32 v40, 1, v81
	v_add3_u32 v41, 0, v41, v40
	s_waitcnt vmcnt(0)
	ds_write_b16 v41, v28 offset:36864
	s_waitcnt lgkmcnt(1)
	v_add_f32_e32 v42, v42, v43
	s_nop 1
	v_mov_b32_dpp v43, v42 row_half_mirror row_mask:0xf bank_mask:0xf
	ds_write_b16_d16_hi v41, v28 offset:37408
	ds_write_b16 v41, v29 offset:37952
	ds_write_b16_d16_hi v41, v29 offset:38496
	ds_write_b16 v41, v30 offset:39040
	ds_write_b16_d16_hi v41, v30 offset:39584
	ds_write_b16 v41, v31 offset:40128
	ds_write_b16_d16_hi v41, v31 offset:40672
	v_add_u32_e32 v41, 0x200, v158
	v_ashrrev_i32_e32 v83, 3, v41
	v_mad_u64_u32 v[44:45], s[4:5], v83, s69, v[152:153]
	ds_write_b128 v44, v[32:35]
	s_and_saveexec_b64 s[48:49], vcc
	s_cbranch_execz .LBB0_180
	s_waitcnt lgkmcnt(8)
	v_add_f32_e32 v42, v42, v43
	v_fmamk_f32 v42, v42, 0x3c800000, v243
	v_cmp_gt_f32_e64 s[4:5], s88, v42
	v_mul_f32_e32 v43, 0x4b800000, v42
	s_nop 0
	v_cndmask_b32_e64 v42, v42, v43, s[4:5]
	v_rsq_f32_e32 v42, v42
	s_nop 0
	v_mul_f32_e32 v43, 0x45800000, v42
	v_cndmask_b32_e64 v42, v42, v43, s[4:5]
	v_lshl_add_u32 v43, v83, 2, 0
	v_add_u32_e32 v43, 0x11800, v43
	ds_write_b32 v43, v42
.LBB0_180:
	s_or_b64 exec, exec, s[48:49]
	s_waitcnt lgkmcnt(8)
	v_and_b32_e32 v43, 0xffff0000, v24
	v_lshlrev_b32_e32 v42, 16, v24
	v_mul_f32_e32 v43, v43, v43
	v_and_b32_e32 v44, 0xffff0000, v25
	v_fmac_f32_e32 v43, v42, v42
	v_lshlrev_b32_e32 v42, 16, v25
	v_mul_f32_e32 v44, v44, v44
	v_fmac_f32_e32 v44, v42, v42
	v_add_f32_e32 v42, v43, v44
	v_and_b32_e32 v44, 0xffff0000, v26
	v_lshlrev_b32_e32 v43, 16, v26
	v_mul_f32_e32 v44, v44, v44
	v_fmac_f32_e32 v44, v43, v43
	v_add_f32_e32 v42, v44, v42
	v_and_b32_e32 v44, 0xffff0000, v27
	v_lshlrev_b32_e32 v43, 16, v27
	v_mul_f32_e32 v44, v44, v44
	v_fmac_f32_e32 v44, v43, v43
	v_add_f32_e32 v42, v44, v42
	s_nop 1
	v_mov_b32_dpp v43, v42 quad_perm:[1,0,3,2] row_mask:0xf bank_mask:0xf
	v_ashrrev_i32_e32 v41, 5, v41
	v_and_b32_e32 v82, -8, v41
	v_mul_lo_u32 v41, v82, s0
	v_add3_u32 v41, 0, v41, v40
	s_waitcnt lgkmcnt(0)
	v_add_f32_e32 v42, v42, v43
	s_nop 1
	v_mov_b32_dpp v43, v42 quad_perm:[2,3,0,1] row_mask:0xf bank_mask:0xf
	ds_write_b16 v41, v20 offset:36864
	ds_write_b16_d16_hi v41, v20 offset:37408
	ds_write_b16 v41, v21 offset:37952
	ds_write_b16_d16_hi v41, v21 offset:38496
	ds_write_b16 v41, v22 offset:39040
	ds_write_b16_d16_hi v41, v22 offset:39584
	ds_write_b16 v41, v23 offset:40128
	ds_write_b16_d16_hi v41, v23 offset:40672
	v_add_u32_e32 v41, 0x400, v158
	s_waitcnt lgkmcnt(8)
	v_add_f32_e32 v42, v42, v43
	s_nop 1
	v_mov_b32_dpp v43, v42 row_half_mirror row_mask:0xf bank_mask:0xf
	v_ashrrev_i32_e32 v85, 3, v41
	v_mad_u64_u32 v[44:45], s[4:5], v85, s69, v[152:153]
	ds_write_b128 v44, v[24:27]
	s_and_saveexec_b64 s[48:49], vcc
	s_cbranch_execz .LBB0_182
	s_waitcnt lgkmcnt(1)
	v_add_f32_e32 v42, v42, v43
	v_fmamk_f32 v42, v42, 0x3c800000, v243
	v_cmp_gt_f32_e64 s[4:5], s88, v42
	v_mul_f32_e32 v43, 0x4b800000, v42
	s_nop 0
	v_cndmask_b32_e64 v42, v42, v43, s[4:5]
	v_rsq_f32_e32 v42, v42
	s_nop 0
	v_mul_f32_e32 v43, 0x45800000, v42
	v_cndmask_b32_e64 v42, v42, v43, s[4:5]
	v_lshl_add_u32 v43, v85, 2, 0
	v_add_u32_e32 v43, 0x11800, v43
	ds_write_b32 v43, v42
.LBB0_182:
	s_or_b64 exec, exec, s[48:49]
	s_waitcnt lgkmcnt(1)
	v_and_b32_e32 v43, 0xffff0000, v16
	v_lshlrev_b32_e32 v42, 16, v16
	v_mul_f32_e32 v43, v43, v43
	v_and_b32_e32 v44, 0xffff0000, v17
	v_fmac_f32_e32 v43, v42, v42
	v_lshlrev_b32_e32 v42, 16, v17
	v_mul_f32_e32 v44, v44, v44
	v_fmac_f32_e32 v44, v42, v42
	v_add_f32_e32 v42, v43, v44
	v_and_b32_e32 v44, 0xffff0000, v18
	v_lshlrev_b32_e32 v43, 16, v18
	v_mul_f32_e32 v44, v44, v44
	v_fmac_f32_e32 v44, v43, v43
	v_add_f32_e32 v42, v44, v42
	v_and_b32_e32 v44, 0xffff0000, v19
	v_lshlrev_b32_e32 v43, 16, v19
	v_mul_f32_e32 v44, v44, v44
	v_fmac_f32_e32 v44, v43, v43
	v_add_f32_e32 v42, v44, v42
	s_nop 1
	v_mov_b32_dpp v43, v42 quad_perm:[1,0,3,2] row_mask:0xf bank_mask:0xf
	v_ashrrev_i32_e32 v41, 5, v41
	v_and_b32_e32 v84, -8, v41
	v_mul_lo_u32 v41, v84, s0
	v_add3_u32 v41, 0, v41, v40
	s_waitcnt lgkmcnt(0)
	v_add_f32_e32 v42, v42, v43
	s_nop 1
	v_mov_b32_dpp v43, v42 quad_perm:[2,3,0,1] row_mask:0xf bank_mask:0xf
	ds_write_b16 v41, v12 offset:36864
	ds_write_b16_d16_hi v41, v12 offset:37408
	ds_write_b16 v41, v13 offset:37952
	ds_write_b16_d16_hi v41, v13 offset:38496
	ds_write_b16 v41, v14 offset:39040
	ds_write_b16_d16_hi v41, v14 offset:39584
	ds_write_b16 v41, v15 offset:40128
	ds_write_b16_d16_hi v41, v15 offset:40672
	v_add_u32_e32 v41, 0x600, v158
	s_waitcnt lgkmcnt(8)
	v_add_f32_e32 v42, v42, v43
	s_nop 1
	v_mov_b32_dpp v43, v42 row_half_mirror row_mask:0xf bank_mask:0xf
	v_ashrrev_i32_e32 v87, 3, v41
	v_mad_u64_u32 v[44:45], s[4:5], v87, s69, v[152:153]
	ds_write_b128 v44, v[16:19]
	s_and_saveexec_b64 s[4:5], vcc
	s_cbranch_execz .LBB0_184
	s_waitcnt lgkmcnt(1)
	v_add_f32_e32 v42, v42, v43
	v_fmamk_f32 v42, v42, 0x3c800000, v243
	v_cmp_gt_f32_e32 vcc, s88, v42
	v_mul_f32_e32 v43, 0x4b800000, v42
	s_nop 0
	v_cndmask_b32_e32 v42, v42, v43, vcc
	v_rsq_f32_e32 v42, v42
	s_nop 0
	v_mul_f32_e32 v43, 0x45800000, v42
	v_cndmask_b32_e32 v42, v42, v43, vcc
	v_lshl_add_u32 v43, v87, 2, 0
	v_add_u32_e32 v43, 0x11800, v43
	ds_write_b32 v43, v42

.LBB0_189:
	s_and_b64 vcc, exec, s[4:5]
	s_cbranch_vccz .LBB0_167
	s_waitcnt vmcnt(23)
	v_mul_f32_e32 v40, v185, v185
	v_mul_f32_e32 v41, v167, v167
	v_fmac_f32_e32 v40, v165, v165
	v_fmac_f32_e32 v41, v164, v164
	v_add_f32_e32 v40, v40, v41
	v_mul_f32_e32 v41, v166, v166
	v_fmac_f32_e32 v41, v162, v162
	v_add_f32_e32 v40, v41, v40
	v_mul_f32_e32 v41, v163, v163
	v_fmac_f32_e32 v41, v161, v161
	v_add_f32_e32 v40, v41, v40
	s_nop 1
	v_mov_b32_dpp v41, v40 quad_perm:[1,0,3,2] row_mask:0xf bank_mask:0xf
	s_mov_b64 s[14:15], s[86:87]
	s_load_dwordx2 s[86:87], s[62:63], 0xd8
	s_load_dwordx4 s[8:11], s[62:63], 0xf8
	v_cmp_eq_u32_e32 vcc, 0, v160
	v_mad_u64_u32 v[42:43], s[4:5], v159, s69, v[152:153]
	s_waitcnt lgkmcnt(0)
	v_add_f32_e32 v40, v40, v41
	s_nop 1
	v_mov_b32_dpp v41, v40 quad_perm:[2,3,0,1] row_mask:0xf bank_mask:0xf
	s_waitcnt lgkmcnt(0)
	s_barrier
	ds_write_b128 v42, v[36:39]
	v_add_f32_e32 v40, v40, v41
	s_nop 1
	v_mov_b32_dpp v41, v40 row_half_mirror row_mask:0xf bank_mask:0xf
	s_and_saveexec_b64 s[48:49], vcc
	s_cbranch_execz .LBB0_192
	s_waitcnt lgkmcnt(0)
	v_add_f32_e32 v40, v40, v41
	v_fmamk_f32 v40, v40, 0x3c800000, v243
	v_cmp_gt_f32_e64 s[4:5], s88, v40
	v_mul_f32_e32 v41, 0x4b800000, v40
	s_nop 0
	v_cndmask_b32_e64 v40, v40, v41, s[4:5]
	v_rsq_f32_e32 v40, v40
	s_nop 0
	v_mul_f32_e32 v41, 0x45800000, v40
	v_cndmask_b32_e64 v40, v40, v41, s[4:5]
	v_lshl_add_u32 v41, v159, 2, 0
	v_add_u32_e32 v41, 0x11800, v41
	ds_write_b32 v41, v40
.LBB0_192:
	s_or_b64 exec, exec, s[48:49]
	v_and_b32_e32 v43, 0xffff0000, v32
	v_lshlrev_b32_e32 v42, 16, v32
	v_mul_f32_e32 v43, v43, v43
	s_waitcnt vmcnt(22)
	v_and_b32_e32 v44, 0xffff0000, v33
	v_fmac_f32_e32 v43, v42, v42
	v_lshlrev_b32_e32 v42, 16, v33
	v_mul_f32_e32 v44, v44, v44
	v_fmac_f32_e32 v44, v42, v42
	v_add_f32_e32 v42, v43, v44
	v_and_b32_e32 v44, 0xffff0000, v34
	v_lshlrev_b32_e32 v43, 16, v34
	v_mul_f32_e32 v44, v44, v44
	v_fmac_f32_e32 v44, v43, v43
	v_add_f32_e32 v42, v44, v42
	v_and_b32_e32 v44, 0xffff0000, v35
	v_lshlrev_b32_e32 v43, 16, v35
	v_mul_f32_e32 v44, v44, v44
	v_fmac_f32_e32 v44, v43, v43
	v_add_f32_e32 v42, v44, v42
	s_nop 1
	v_mov_b32_dpp v43, v42 quad_perm:[1,0,3,2] row_mask:0xf bank_mask:0xf
	v_ashrrev_i32_e32 v40, 5, v158
	s_waitcnt vmcnt(20)
	v_and_b32_e32 v53, 0xff, v158
	v_and_b32_e32 v52, -8, v40
	s_movk_i32 s0, 0x220
	s_waitcnt lgkmcnt(0)
	v_add_f32_e32 v42, v42, v43
	s_nop 1
	v_mov_b32_dpp v43, v42 quad_perm:[2,3,0,1] row_mask:0xf bank_mask:0xf
	v_mul_lo_u32 v41, v52, s0
	v_lshlrev_b32_e32 v40, 1, v53
	v_add3_u32 v41, 0, v41, v40
	s_waitcnt vmcnt(0)
	ds_write_b16 v41, v28 offset:36864
	s_waitcnt lgkmcnt(1)
	v_add_f32_e32 v42, v42, v43
	s_nop 1
	v_mov_b32_dpp v43, v42 row_half_mirror row_mask:0xf bank_mask:0xf
	ds_write_b16_d16_hi v41, v28 offset:37408
	ds_write_b16 v41, v29 offset:37952
	ds_write_b16_d16_hi v41, v29 offset:38496
	ds_write_b16 v41, v30 offset:39040
	ds_write_b16_d16_hi v41, v30 offset:39584
	ds_write_b16 v41, v31 offset:40128
	ds_write_b16_d16_hi v41, v31 offset:40672
	v_add_u32_e32 v41, 0x200, v158
	v_ashrrev_i32_e32 v55, 3, v41
	v_mad_u64_u32 v[44:45], s[4:5], v55, s69, v[152:153]
	ds_write_b128 v44, v[32:35]
	s_and_saveexec_b64 s[48:49], vcc
	s_cbranch_execz .LBB0_194
	s_waitcnt lgkmcnt(8)
	v_add_f32_e32 v42, v42, v43
	v_fmamk_f32 v42, v42, 0x3c800000, v243
	v_cmp_gt_f32_e64 s[4:5], s88, v42
	v_mul_f32_e32 v43, 0x4b800000, v42
	s_nop 0
	v_cndmask_b32_e64 v42, v42, v43, s[4:5]
	v_rsq_f32_e32 v42, v42
	s_nop 0
	v_mul_f32_e32 v43, 0x45800000, v42
	v_cndmask_b32_e64 v42, v42, v43, s[4:5]
	v_lshl_add_u32 v43, v55, 2, 0
	v_add_u32_e32 v43, 0x11800, v43
	ds_write_b32 v43, v42
.LBB0_194:
	s_or_b64 exec, exec, s[48:49]
	s_waitcnt lgkmcnt(8)
	v_and_b32_e32 v43, 0xffff0000, v24
	v_lshlrev_b32_e32 v42, 16, v24
	v_mul_f32_e32 v43, v43, v43
	v_and_b32_e32 v44, 0xffff0000, v25
	v_fmac_f32_e32 v43, v42, v42
	v_lshlrev_b32_e32 v42, 16, v25
	v_mul_f32_e32 v44, v44, v44
	v_fmac_f32_e32 v44, v42, v42
	v_add_f32_e32 v42, v43, v44
	v_and_b32_e32 v44, 0xffff0000, v26
	v_lshlrev_b32_e32 v43, 16, v26
	v_mul_f32_e32 v44, v44, v44
	v_fmac_f32_e32 v44, v43, v43
	v_add_f32_e32 v42, v44, v42
	v_and_b32_e32 v44, 0xffff0000, v27
	v_lshlrev_b32_e32 v43, 16, v27
	v_mul_f32_e32 v44, v44, v44
	v_fmac_f32_e32 v44, v43, v43
	v_add_f32_e32 v42, v44, v42
	s_nop 1
	v_mov_b32_dpp v43, v42 quad_perm:[1,0,3,2] row_mask:0xf bank_mask:0xf
	v_ashrrev_i32_e32 v41, 5, v41
	v_and_b32_e32 v54, -8, v41
	v_mul_lo_u32 v41, v54, s0
	v_add3_u32 v41, 0, v41, v40
	s_waitcnt lgkmcnt(0)
	v_add_f32_e32 v42, v42, v43
	s_nop 1
	v_mov_b32_dpp v43, v42 quad_perm:[2,3,0,1] row_mask:0xf bank_mask:0xf
	ds_write_b16 v41, v20 offset:36864
	ds_write_b16_d16_hi v41, v20 offset:37408
	ds_write_b16 v41, v21 offset:37952
	ds_write_b16_d16_hi v41, v21 offset:38496
	ds_write_b16 v41, v22 offset:39040
	ds_write_b16_d16_hi v41, v22 offset:39584
	ds_write_b16 v41, v23 offset:40128
	ds_write_b16_d16_hi v41, v23 offset:40672
	v_add_u32_e32 v41, 0x400, v158
	s_waitcnt lgkmcnt(8)
	v_add_f32_e32 v42, v42, v43
	s_nop 1
	v_mov_b32_dpp v43, v42 row_half_mirror row_mask:0xf bank_mask:0xf
	v_ashrrev_i32_e32 v57, 3, v41
	v_mad_u64_u32 v[44:45], s[4:5], v57, s69, v[152:153]
	ds_write_b128 v44, v[24:27]
	s_and_saveexec_b64 s[48:49], vcc
	s_cbranch_execz .LBB0_196
	s_waitcnt lgkmcnt(1)
	v_add_f32_e32 v42, v42, v43
	v_fmamk_f32 v42, v42, 0x3c800000, v243
	v_cmp_gt_f32_e64 s[4:5], s88, v42
	v_mul_f32_e32 v43, 0x4b800000, v42
	s_nop 0
	v_cndmask_b32_e64 v42, v42, v43, s[4:5]
	v_rsq_f32_e32 v42, v42
	s_nop 0
	v_mul_f32_e32 v43, 0x45800000, v42
	v_cndmask_b32_e64 v42, v42, v43, s[4:5]
	v_lshl_add_u32 v43, v57, 2, 0
	v_add_u32_e32 v43, 0x11800, v43
	ds_write_b32 v43, v42
.LBB0_196:
	s_or_b64 exec, exec, s[48:49]
	v_ashrrev_i32_e32 v41, 5, v41
	v_and_b32_e32 v56, -8, v41
	v_mul_lo_u32 v41, v56, s0
	v_add3_u32 v41, 0, v41, v40
	ds_write_b16 v41, v12 offset:36864
	ds_write_b16_d16_hi v41, v12 offset:37408
	ds_write_b16 v41, v13 offset:37952
	ds_write_b16_d16_hi v41, v13 offset:38496
	ds_write_b16 v41, v14 offset:39040
	ds_write_b16_d16_hi v41, v14 offset:39584
	ds_write_b16 v41, v15 offset:40128
	ds_write_b16_d16_hi v41, v15 offset:40672
	v_add_u32_e32 v41, 0x600, v158
	v_ashrrev_i32_e32 v59, 3, v41
	s_waitcnt lgkmcnt(9)
	v_mad_u64_u32 v[42:43], s[4:5], v59, s69, v[152:153]
	v_and_b32_e32 v43, 0xffff0000, v16
	ds_write_b128 v42, v[16:19]
	v_lshlrev_b32_e32 v42, 16, v16
	v_mul_f32_e32 v43, v43, v43
	v_and_b32_e32 v44, 0xffff0000, v17
	v_fmac_f32_e32 v43, v42, v42
	v_lshlrev_b32_e32 v42, 16, v17
	v_mul_f32_e32 v44, v44, v44
	v_fmac_f32_e32 v44, v42, v42
	v_add_f32_e32 v42, v43, v44
	v_and_b32_e32 v44, 0xffff0000, v18
	v_lshlrev_b32_e32 v43, 16, v18
	v_mul_f32_e32 v44, v44, v44
	v_fmac_f32_e32 v44, v43, v43
	v_add_f32_e32 v42, v44, v42
	v_and_b32_e32 v44, 0xffff0000, v19
	v_lshlrev_b32_e32 v43, 16, v19
	v_mul_f32_e32 v44, v44, v44
	v_fmac_f32_e32 v44, v43, v43
	v_add_f32_e32 v42, v44, v42
	s_nop 1
	v_mov_b32_dpp v43, v42 quad_perm:[1,0,3,2] row_mask:0xf bank_mask:0xf
	s_waitcnt lgkmcnt(0)
	v_add_f32_e32 v42, v42, v43
	s_nop 1
	v_mov_b32_dpp v43, v42 quad_perm:[2,3,0,1] row_mask:0xf bank_mask:0xf
	s_waitcnt lgkmcnt(0)
	v_add_f32_e32 v42, v42, v43
	s_nop 1
	v_mov_b32_dpp v43, v42 row_half_mirror row_mask:0xf bank_mask:0xf
	s_and_saveexec_b64 s[4:5], vcc
	s_cbranch_execz .LBB0_198
	s_waitcnt lgkmcnt(0)
	v_add_f32_e32 v42, v42, v43
	v_fmamk_f32 v42, v42, 0x3c800000, v243
	v_cmp_gt_f32_e32 vcc, s88, v42
	v_mul_f32_e32 v43, 0x4b800000, v42
	s_nop 0
	v_cndmask_b32_e32 v42, v42, v43, vcc
	v_rsq_f32_e32 v42, v42
	s_nop 0
	v_mul_f32_e32 v43, 0x45800000, v42
	v_cndmask_b32_e32 v42, v42, v43, vcc
	v_lshl_add_u32 v43, v59, 2, 0
	v_add_u32_e32 v43, 0x11800, v43
	ds_write_b32 v43, v42
